# v13 + FFN-up phases: CU groups (blockIdx>>3)&7 start staggered by g*90*64 clocks so tile epilogue store bursts / MFMA power of the groups do not coincide
# speedup vs baseline: 1.0009x; 1.0009x over previous
; __global__ void __launch_bounds__(512) fwd_megakernel(Args a) {
;     ...
;         float* ssq0 = PH0; float* ssq1 = PH1; float* ssq2 = PH2; float* ssq3 = PH3; float* ssq4 = PH0;
;         { pg8::Gemm g{(L == 0) ? HB : (const bf16_t*)QA, Wb + W_GU1, MTOK, 2 * DFF, DM, DM}; pg8::StaticOrder S; S.init(MTOK, 2 * DFF, G, bx);
;           pg8::EpiSwiglu E{HID, ssq0}; pg8::gemm_phase(lds, wave_s, g, S, E); }
.LBB0_156:
	v_readlane_b32 s98, v252, 36
	s_nop 3
	s_lshr_b32 s98, s98, 3
	s_and_b32 s98, s98, 7
.Ldsy_156_loop:
	s_cmp_eq_u32 s98, 0
	s_cbranch_scc1 .Ldsy_156_done
	s_sleep 90
	s_sub_u32 s98, s98, 1
	s_branch .Ldsy_156_loop
